# nt hint on the read-once residual loads of the output-projection epilogue
# baseline (speedup 1.0000x reference)
; template <int PH>
; DI void epilogue(const Params& p, const f32x4 (&acc)[2][2][4][2], const Unit& u, int wr, int wc, int fr, int fq) {
;     ...
; #pragma unroll
;         for (int ai = 0; ai < 2; ++ai) {
;             f32x4 xv[4][2][2];
; #pragma unroll
;             for (int m = 0; m < 4; ++m) {
;                 const int r = u.pm * 256 + rl0 + 128 * ai + 16 * m;
;                 const float* xr = (r < T_P ? p.x_prompt + (size_t)r * 1024 : p.x_sample + (size_t)(r - T_P) * 1024) + u.coff + cl0;
; #pragma unroll
;                 for (int bj = 0; bj < 2; ++bj)
; #pragma unroll
;                     for (int n = 0; n < 2; ++n) xv[m][bj][n] = *(const f32x4*)(xr + 32 * bj + 4 * n);
;             }
; #pragma unroll
;             for (int m = 0; m < 4; ++m) {
;                 const int r = u.pm * 256 + rl0 + 128 * ai + 16 * m;
;                 float* yr = p.out + O_Y + (size_t)r * 1024 + u.coff + cl0;
; #pragma unroll
;                 for (int bj = 0; bj < 2; ++bj)
; #pragma unroll
;                     for (int n = 0; n < 2; ++n) *(f32x4*)(yr + 32 * bj + 4 * n) = acc[ai][bj][m][n] + xv[m][bj][n];
;             }
.LBB0_1379:
	v_lshl_add_u32 v206, s22, 8, v214
	v_add_u32_e32 v128, 0xffffc000, v206
	v_ashrrev_i32_e32 v207, 31, v206
	v_cmp_gt_i32_e32 vcc, s43, v206
	v_mov_b32_e32 v132, s7
	v_mov_b32_e32 v133, s5
	v_cndmask_b32_e32 v129, 0, v207, vcc
	v_cndmask_b32_e32 v128, v128, v206, vcc
	v_mov_b32_e32 v134, s6
	v_mov_b32_e32 v135, s4
	s_ashr_i32 s25, s24, 31
	v_cndmask_b32_e32 v131, v132, v133, vcc
	v_cndmask_b32_e32 v130, v134, v135, vcc
	v_lshlrev_b64 v[128:129], 12, v[128:129]
	v_lshl_add_u64 v[128:129], v[130:131], 0, v[128:129]
	s_lshl_b64 s[22:23], s[24:25], 2
	v_lshl_add_u64 v[128:129], v[128:129], 0, s[22:23]
	v_lshl_add_u64 v[128:129], v[128:129], 0, v[200:201]
	v_or_b32_e32 v212, 16, v206
	global_load_dwordx4 v[184:187], v[128:129], off offset:16 nt
	global_load_dwordx4 v[188:191], v[128:129], off nt
	global_load_dwordx4 v[172:175], v[128:129], off offset:144 nt
	global_load_dwordx4 v[180:183], v[128:129], off offset:128 nt
	v_ashrrev_i32_e32 v213, 31, v212
	v_add_u32_e32 v128, 0xffffc010, v206
	v_cmp_gt_i32_e32 vcc, s43, v212
	v_or_b32_e32 v210, 32, v206
	v_ashrrev_i32_e32 v211, 31, v210
	v_cndmask_b32_e32 v129, 0, v213, vcc
	v_cndmask_b32_e32 v128, v128, v212, vcc
	v_cndmask_b32_e32 v131, v132, v133, vcc
	v_cndmask_b32_e32 v130, v134, v135, vcc
	v_lshlrev_b64 v[128:129], 12, v[128:129]
	v_lshl_add_u64 v[128:129], v[130:131], 0, v[128:129]
	v_lshl_add_u64 v[128:129], v[128:129], 0, s[22:23]
	v_lshl_add_u64 v[128:129], v[128:129], 0, v[200:201]
	global_load_dwordx4 v[168:171], v[128:129], off offset:16 nt
	global_load_dwordx4 v[176:179], v[128:129], off nt
	global_load_dwordx4 v[156:159], v[128:129], off offset:144 nt
	global_load_dwordx4 v[164:167], v[128:129], off offset:128 nt
	v_add_u32_e32 v128, 0xffffc020, v206
	v_cmp_gt_i32_e32 vcc, s43, v210
	s_nop 1
	v_cndmask_b32_e32 v129, 0, v211, vcc
	v_cndmask_b32_e32 v128, v128, v210, vcc
	v_cndmask_b32_e32 v131, v132, v133, vcc
	v_cndmask_b32_e32 v130, v134, v135, vcc
	v_lshlrev_b64 v[128:129], 12, v[128:129]
	v_lshl_add_u64 v[128:129], v[130:131], 0, v[128:129]
	v_lshl_add_u64 v[128:129], v[128:129], 0, s[22:23]
	v_lshl_add_u64 v[128:129], v[128:129], 0, v[200:201]
	global_load_dwordx4 v[152:155], v[128:129], off offset:16 nt
	global_load_dwordx4 v[160:163], v[128:129], off nt
	global_load_dwordx4 v[144:147], v[128:129], off offset:144 nt
	global_load_dwordx4 v[148:151], v[128:129], off offset:128 nt
	v_or_b32_e32 v130, 48, v206
	v_cmp_lt_i32_e32 vcc, s48, v130
	s_and_saveexec_b64 s[24:25], vcc
	s_xor_b64 s[24:25], exec, s[24:25]
	v_add_u32_e32 v128, 0xffffc030, v206
	v_mov_b32_e32 v129, v201
	v_lshlrev_b64 v[128:129], 12, v[128:129]
	v_mov_b32_e32 v131, v201
	v_lshl_add_u64 v[128:129], s[6:7], 0, v[128:129]
	v_lshlrev_b64 v[208:209], 12, v[130:131]
	s_andn2_saveexec_b64 s[24:25], s[24:25]
	v_ashrrev_i32_e32 v131, 31, v130
	v_lshlrev_b64 v[208:209], 12, v[130:131]
	v_lshl_add_u64 v[128:129], s[4:5], 0, v[208:209]
	s_or_b64 exec, exec, s[24:25]
	v_lshl_add_u64 v[128:129], v[128:129], 0, s[22:23]
	v_lshl_add_u64 v[128:129], v[128:129], 0, v[200:201]
	global_load_dwordx4 v[140:143], v[128:129], off nt
	global_load_dwordx4 v[132:135], v[128:129], off offset:16 nt
	global_load_dwordx4 v[136:139], v[128:129], off offset:128 nt
	s_nop 0
	global_load_dwordx4 v[128:131], v[128:129], off offset:144 nt
	v_lshlrev_b64 v[220:221], 12, v[206:207]
	s_waitcnt vmcnt(0)
	v_pk_add_f32 v[180:181], v[116:117], v[180:181]
	v_add_u32_e32 v116, 0x80, v206
	v_pk_add_f32 v[182:183], v[118:119], v[182:183]
	v_lshlrev_b64 v[118:119], 12, v[212:213]
	v_pk_add_f32 v[92:93], v[92:93], v[156:157]
	v_lshlrev_b64 v[156:157], 12, v[210:211]
	v_pk_add_f32 v[86:87], v[86:87], v[150:151]
	v_pk_add_f32 v[82:83], v[82:83], v[146:147]
	v_add_u32_e32 v150, 0xffffc080, v206
	v_lshl_add_u64 v[146:147], s[14:15], 0, v[220:221]
	v_ashrrev_i32_e32 v117, 31, v116
	v_cmp_gt_i32_e32 vcc, s49, v206
	v_pk_add_f32 v[94:95], v[94:95], v[158:159]
	v_pk_add_f32 v[90:91], v[90:91], v[154:155]
	v_pk_add_f32 v[84:85], v[84:85], v[148:149]
	v_mov_b32_e32 v154, s7
	v_mov_b32_e32 v155, s5
	v_mov_b32_e32 v158, s6
	v_mov_b32_e32 v159, s4
	v_lshl_add_u64 v[118:119], s[14:15], 0, v[118:119]
	v_lshl_add_u64 v[148:149], s[14:15], 0, v[156:157]
	v_lshl_add_u64 v[146:147], v[146:147], 0, s[22:23]
	v_cndmask_b32_e32 v151, 0, v117, vcc
	v_cndmask_b32_e32 v150, v150, v116, vcc
	v_pk_add_f32 v[126:127], v[126:127], v[190:191]
	v_pk_add_f32 v[124:125], v[124:125], v[188:189]
	v_pk_add_f32 v[88:89], v[88:89], v[152:153]
	v_pk_add_f32 v[80:81], v[80:81], v[144:145]
	v_lshl_add_u64 v[144:145], s[14:15], 0, v[208:209]
	v_lshl_add_u64 v[118:119], v[118:119], 0, s[22:23]
	v_lshl_add_u64 v[148:149], v[148:149], 0, s[22:23]
	v_cndmask_b32_e32 v153, v154, v155, vcc
	v_cndmask_b32_e32 v152, v158, v159, vcc
	v_lshl_add_u64 v[146:147], v[146:147], 0, v[200:201]
	v_lshlrev_b64 v[150:151], 12, v[150:151]
	v_pk_add_f32 v[122:123], v[122:123], v[186:187]
	v_pk_add_f32 v[120:121], v[120:121], v[184:185]
	v_pk_add_f32 v[110:111], v[110:111], v[174:175]
	v_pk_add_f32 v[108:109], v[108:109], v[172:173]
	v_pk_add_f32 v[114:115], v[114:115], v[178:179]
	v_pk_add_f32 v[112:113], v[112:113], v[176:177]
	v_pk_add_f32 v[106:107], v[106:107], v[170:171]
	v_pk_add_f32 v[104:105], v[104:105], v[168:169]
	v_pk_add_f32 v[102:103], v[102:103], v[166:167]
	v_pk_add_f32 v[100:101], v[100:101], v[164:165]
	v_pk_add_f32 v[98:99], v[98:99], v[162:163]
	v_pk_add_f32 v[96:97], v[96:97], v[160:161]
	v_lshl_add_u64 v[144:145], v[144:145], 0, s[22:23]
	v_lshl_add_u64 v[118:119], v[118:119], 0, v[200:201]
	v_lshl_add_u64 v[148:149], v[148:149], 0, v[200:201]
	global_store_dwordx4 v[146:147], v[124:127], off
; template <int PH>
; DI void epilogue(const Params& p, const f32x4 (&acc)[2][2][4][2], const Unit& u, int wr, int wc, int fr, int fq) {
;     ...
; #pragma unroll
;         for (int ai = 0; ai < 2; ++ai) {
;             f32x4 xv[4][2][2];
; #pragma unroll
;             for (int m = 0; m < 4; ++m) {
;                 const int r = u.pm * 256 + rl0 + 128 * ai + 16 * m;
;                 const float* xr = (r < T_P ? p.x_prompt + (size_t)r * 1024 : p.x_sample + (size_t)(r - T_P) * 1024) + u.coff + cl0;
; #pragma unroll
;                 for (int bj = 0; bj < 2; ++bj)
; #pragma unroll
;                     for (int n = 0; n < 2; ++n) xv[m][bj][n] = *(const f32x4*)(xr + 32 * bj + 4 * n);
;             }
; #pragma unroll
;             for (int m = 0; m < 4; ++m) {
;                 const int r = u.pm * 256 + rl0 + 128 * ai + 16 * m;
;                 float* yr = p.out + O_Y + (size_t)r * 1024 + u.coff + cl0;
; #pragma unroll
;                 for (int bj = 0; bj < 2; ++bj)
; #pragma unroll
;                     for (int n = 0; n < 2; ++n) *(f32x4*)(yr + 32 * bj + 4 * n) = acc[ai][bj][m][n] + xv[m][bj][n];
;             }
	global_store_dwordx4 v[146:147], v[120:123], off offset:16
	global_store_dwordx4 v[146:147], v[180:183], off offset:128
	global_store_dwordx4 v[146:147], v[108:111], off offset:144
	global_store_dwordx4 v[118:119], v[112:115], off
	global_store_dwordx4 v[118:119], v[104:107], off offset:16
	global_store_dwordx4 v[118:119], v[100:103], off offset:128
	global_store_dwordx4 v[118:119], v[92:95], off offset:144
	global_store_dwordx4 v[148:149], v[96:99], off
	global_store_dwordx4 v[148:149], v[88:91], off offset:16
	global_store_dwordx4 v[148:149], v[84:87], off offset:128
	global_store_dwordx4 v[148:149], v[80:83], off offset:144
	v_lshl_add_u64 v[144:145], v[144:145], 0, v[200:201]
	v_add_u32_e32 v118, 0x90, v206
	v_lshl_add_u64 v[80:81], v[152:153], 0, v[150:151]
	v_lshl_add_u64 v[80:81], v[80:81], 0, s[22:23]
	v_ashrrev_i32_e32 v119, 31, v118
	v_cmp_gt_i32_e32 vcc, s50, v206
	v_add_u32_e32 v114, 0xa0, v206
	v_ashrrev_i32_e32 v115, 31, v114
	v_add_u32_e32 v122, 0xb0, v206
	v_pk_add_f32 v[78:79], v[78:79], v[142:143]
	v_pk_add_f32 v[76:77], v[76:77], v[140:141]
	v_pk_add_f32 v[74:75], v[74:75], v[134:135]
	v_pk_add_f32 v[64:65], v[64:65], v[128:129]
	v_pk_add_f32 v[72:73], v[72:73], v[132:133]
	v_pk_add_f32 v[70:71], v[70:71], v[138:139]
	v_pk_add_f32 v[68:69], v[68:69], v[136:137]
	v_pk_add_f32 v[66:67], v[66:67], v[130:131]
	global_store_dwordx4 v[144:145], v[76:79], off
	global_store_dwordx4 v[144:145], v[72:75], off offset:16
	global_store_dwordx4 v[144:145], v[68:71], off offset:128
	global_store_dwordx4 v[144:145], v[64:67], off offset:144
	s_nop 1
	v_lshl_add_u64 v[64:65], v[80:81], 0, v[200:201]
	global_load_dwordx4 v[104:107], v[64:65], off offset:16 nt
	global_load_dwordx4 v[108:111], v[64:65], off nt
	global_load_dwordx4 v[92:95], v[64:65], off offset:144 nt
	global_load_dwordx4 v[100:103], v[64:65], off offset:128 nt
	v_add_u32_e32 v64, 0xffffc090, v206
	v_cndmask_b32_e32 v65, 0, v119, vcc
	v_cndmask_b32_e32 v64, v64, v118, vcc
	v_cndmask_b32_e32 v67, v154, v155, vcc
	v_cndmask_b32_e32 v66, v158, v159, vcc
	v_lshlrev_b64 v[64:65], 12, v[64:65]
	v_lshl_add_u64 v[64:65], v[66:67], 0, v[64:65]
	v_lshl_add_u64 v[64:65], v[64:65], 0, s[22:23]
	v_lshl_add_u64 v[64:65], v[64:65], 0, v[200:201]
	global_load_dwordx4 v[88:91], v[64:65], off offset:16 nt
	global_load_dwordx4 v[96:99], v[64:65], off nt
	global_load_dwordx4 v[76:79], v[64:65], off offset:144 nt
	global_load_dwordx4 v[84:87], v[64:65], off offset:128 nt
	v_add_u32_e32 v64, 0xffffc0a0, v206
	v_cmp_gt_i32_e32 vcc, s51, v206
	s_nop 1
	v_cndmask_b32_e32 v65, 0, v115, vcc
	v_cndmask_b32_e32 v64, v64, v114, vcc
	v_cndmask_b32_e32 v67, v154, v155, vcc
	v_cndmask_b32_e32 v66, v158, v159, vcc
	v_lshlrev_b64 v[64:65], 12, v[64:65]
	v_lshl_add_u64 v[64:65], v[66:67], 0, v[64:65]
	v_lshl_add_u64 v[64:65], v[64:65], 0, s[22:23]
	v_lshl_add_u64 v[68:69], v[64:65], 0, v[200:201]
	global_load_dwordx4 v[72:75], v[68:69], off offset:16 nt
	global_load_dwordx4 v[80:83], v[68:69], off nt
	global_load_dwordx4 v[64:67], v[68:69], off offset:144 nt
	s_nop 0
	global_load_dwordx4 v[68:71], v[68:69], off offset:128 nt
	v_cmp_lt_i32_e32 vcc, s52, v206
	s_and_saveexec_b64 s[24:25], vcc
	s_xor_b64 s[24:25], exec, s[24:25]
	v_add_u32_e32 v112, 0xffffc0b0, v206
	v_mov_b32_e32 v113, v201
	v_lshlrev_b64 v[112:113], 12, v[112:113]
	v_mov_b32_e32 v123, v201
	v_lshl_add_u64 v[120:121], s[6:7], 0, v[112:113]
	v_lshlrev_b64 v[112:113], 12, v[122:123]
	s_andn2_saveexec_b64 s[24:25], s[24:25]
	v_ashrrev_i32_e32 v123, 31, v122
	v_lshlrev_b64 v[112:113], 12, v[122:123]
	v_lshl_add_u64 v[120:121], s[4:5], 0, v[112:113]
	s_or_b64 exec, exec, s[24:25]
	v_lshl_add_u64 v[120:121], v[120:121], 0, s[22:23]
	v_lshl_add_u64 v[132:133], v[120:121], 0, v[200:201]
	global_load_dwordx4 v[120:123], v[132:133], off nt
	global_load_dwordx4 v[124:127], v[132:133], off offset:16 nt
	global_load_dwordx4 v[128:131], v[132:133], off offset:128 nt
	s_nop 0
	global_load_dwordx4 v[132:135], v[132:133], off offset:144 nt
	v_lshlrev_b64 v[116:117], 12, v[116:117]
	s_waitcnt vmcnt(13)
; #define G_BAR __builtin_amdgcn_s_barrier()
; template <int PH>
; DI void epilogue(const Params& p, const f32x4 (&acc)[2][2][4][2], const Unit& u, int wr, int wc, int fr, int fq) {
;     ...
; #pragma unroll
;             for (int m = 0; m < 4; ++m) {
;                 const int r = u.pm * 256 + rl0 + 128 * ai + 16 * m;
;                 float* yr = p.out + O_Y + (size_t)r * 1024 + u.coff + cl0;
; #pragma unroll
;                 for (int bj = 0; bj < 2; ++bj)
; #pragma unroll
;                     for (int n = 0; n < 2; ++n) *(f32x4*)(yr + 32 * bj + 4 * n) = acc[ai][bj][m][n] + xv[m][bj][n];
;             }
;         }
; template <int PH>
; DI void gemm_phase(const Params& p, LAS unsigned char* lds, int mode) {
;     ...
;         if (!has_next) break;
; #pragma unroll
;         for (int a = 0; a < 2; ++a)
; #pragma unroll
;             for (int b = 0; b < 2; ++b)
; #pragma unroll
;                 for (int m = 0; m < 4; ++m)
; #pragma unroll
;                     for (int n = 0; n < 2; ++n) acc[a][b][m][n] = (f32x4){0.f, 0.f, 0.f, 0.f};
;         cur = nxt; cA = nA; cB = nB; cl = nl; ch = nh; ++ui;
;         if (GEMM_ALIGN) { if (wr == 1) G_BAR; }
	v_pk_add_f32 v[44:45], v[44:45], v[92:93]
	v_lshlrev_b64 v[92:93], 12, v[118:119]
	s_waitcnt vmcnt(9)
	v_pk_add_f32 v[28:29], v[28:29], v[76:77]
	v_lshlrev_b64 v[76:77], 12, v[114:115]
	s_waitcnt vmcnt(5)
	v_pk_add_f32 v[18:19], v[18:19], v[66:67]
	v_pk_add_f32 v[16:17], v[16:17], v[64:65]
	v_lshl_add_u64 v[64:65], s[14:15], 0, v[112:113]
	v_lshl_add_u64 v[66:67], s[14:15], 0, v[116:117]
	s_waitcnt vmcnt(4)
	v_pk_add_f32 v[22:23], v[22:23], v[70:71]
	v_pk_add_f32 v[20:21], v[20:21], v[68:69]
	v_lshl_add_u64 v[68:69], s[14:15], 0, v[92:93]
	v_lshl_add_u64 v[70:71], s[14:15], 0, v[76:77]
	v_lshl_add_u64 v[64:65], v[64:65], 0, s[22:23]
	v_lshl_add_u64 v[66:67], v[66:67], 0, s[22:23]
	v_pk_add_f32 v[62:63], v[62:63], v[110:111]
	v_pk_add_f32 v[60:61], v[60:61], v[108:109]
	v_lshl_add_u64 v[68:69], v[68:69], 0, s[22:23]
	v_lshl_add_u64 v[70:71], v[70:71], 0, s[22:23]
	v_lshl_add_u64 v[64:65], v[64:65], 0, v[200:201]
	s_andn2_b64 vcc, exec, s[20:21]
	v_lshl_add_u64 v[66:67], v[66:67], 0, v[200:201]
	s_mov_b64 s[20:21], -1
	v_pk_add_f32 v[58:59], v[58:59], v[106:107]
	v_pk_add_f32 v[56:57], v[56:57], v[104:105]
	v_pk_add_f32 v[54:55], v[54:55], v[102:103]
	v_pk_add_f32 v[52:53], v[52:53], v[100:101]
	v_pk_add_f32 v[46:47], v[46:47], v[94:95]
	v_pk_add_f32 v[50:51], v[50:51], v[98:99]
	v_pk_add_f32 v[48:49], v[48:49], v[96:97]
	v_pk_add_f32 v[42:43], v[42:43], v[90:91]
	v_pk_add_f32 v[40:41], v[40:41], v[88:89]
	v_pk_add_f32 v[38:39], v[38:39], v[86:87]
	v_pk_add_f32 v[36:37], v[36:37], v[84:85]
	v_pk_add_f32 v[30:31], v[30:31], v[78:79]
	v_pk_add_f32 v[34:35], v[34:35], v[82:83]
	v_pk_add_f32 v[32:33], v[32:33], v[80:81]
	v_pk_add_f32 v[26:27], v[26:27], v[74:75]
	v_pk_add_f32 v[24:25], v[24:25], v[72:73]
	v_lshl_add_u64 v[68:69], v[68:69], 0, v[200:201]
	v_lshl_add_u64 v[70:71], v[70:71], 0, v[200:201]
	global_store_dwordx4 v[66:67], v[60:63], off
	global_store_dwordx4 v[66:67], v[56:59], off offset:16
	global_store_dwordx4 v[66:67], v[52:55], off offset:128
	global_store_dwordx4 v[66:67], v[44:47], off offset:144
	global_store_dwordx4 v[68:69], v[48:51], off
	global_store_dwordx4 v[68:69], v[40:43], off offset:16
	global_store_dwordx4 v[68:69], v[36:39], off offset:128
	global_store_dwordx4 v[68:69], v[28:31], off offset:144
	global_store_dwordx4 v[70:71], v[32:35], off
	global_store_dwordx4 v[70:71], v[24:27], off offset:16
	global_store_dwordx4 v[70:71], v[20:23], off offset:128
	global_store_dwordx4 v[70:71], v[16:19], off offset:144
	s_waitcnt vmcnt(15)
	v_pk_add_f32 v[14:15], v[14:15], v[122:123]
	v_pk_add_f32 v[12:13], v[12:13], v[120:121]
	s_waitcnt vmcnt(14)
	v_pk_add_f32 v[10:11], v[10:11], v[126:127]
	v_pk_add_f32 v[8:9], v[8:9], v[124:125]
	s_waitcnt vmcnt(13)
	v_pk_add_f32 v[6:7], v[6:7], v[130:131]
	v_pk_add_f32 v[4:5], v[4:5], v[128:129]
	s_waitcnt vmcnt(12)
	v_pk_add_f32 v[2:3], v[2:3], v[134:135]
	v_pk_add_f32 v[0:1], v[0:1], v[132:133]
	global_store_dwordx4 v[64:65], v[12:15], off
	global_store_dwordx4 v[64:65], v[8:11], off offset:16
	global_store_dwordx4 v[64:65], v[4:7], off offset:128
	global_store_dwordx4 v[64:65], v[0:3], off offset:144
	s_cbranch_vccnz .LBB0_1368
	s_andn2_b64 vcc, exec, s[8:9]
	s_cbranch_vccnz .LBB0_1367
	s_barrier
	s_branch .LBB0_1367
